# P4 epilogue: all per-group gate loads issued at the epilogue head into dead registers, one wait, register moves at the old load sites (on top of the hook hoist)
# baseline (speedup 1.0000x reference)
; __device__ __forceinline__ unsigned cvt_pk_bf16(float lo, float hi) { unsigned r; asm volatile("v_cvt_pk_bf16_f32 %0, %1, %2" : "=v"(r) : "v"(lo), "v"(hi)); return r; }
;     __device__ __forceinline__ void operator()(EPI_ARGS) const {
;         const int col0 = u.pn * 256 + wc * 32 + 8 * fq;
;         u32x2 gc[2], gn[2];
; #pragma unroll
;         for (int bj = 0; bj < 2; ++bj) gc[bj] = *(const u32x2*)(gates + (size_t)ROW_OF(0, 0) * (2 * D) + D + col0 + bj * 128);
; #pragma unroll
;         for (int g = 0; g < 8; ++g) {
;             const int ai = g >> 2, m = g & 3, row = ROW_OF(ai, m);
;             if (g < 7) {
; #pragma unroll
;                 for (int bj = 0; bj < 2; ++bj) gn[bj] = *(const u32x2*)(gates + (size_t)ROW_OF((g + 1) >> 2, (g + 1) & 3) * (2 * D) + D + col0 + bj * 128);
;             }
; #pragma unroll
;             for (int bj = 0; bj < 2; ++bj) {
;                 const unsigned b0 = gc[bj].x, b1 = gc[bj].y;
;                 f32x4 g0, g1;
; #pragma unroll
;                 for (int j = 0; j < 4; ++j) { g0[j] = fmaxf((float)((b0 >> (8 * j)) & 0xff), 0.5f) * (1.0f / 255.0f); g1[j] = fmaxf((float)((b1 >> (8 * j)) & 0xff), 0.5f) * (1.0f / 255.0f); }
;                 const f32x4 v0 = acc[ai][bj][m][0] * g0, v1 = acc[ai][bj][m][1] * g1;
;                 u32x4 w; w.x = cvt_pk_bf16(v0[0], v0[1]); w.y = cvt_pk_bf16(v0[2], v0[3]); w.z = cvt_pk_bf16(v1[0], v1[1]); w.w = cvt_pk_bf16(v1[2], v1[3]);
;                 *(u32x4*)(merged + (size_t)row * D + col0 + bj * 128) = w;
;             }
;             if (g < 7) { gc[0] = gn[0]; gc[1] = gn[1]; }
;         }
;     }
.LBB0_757:
	v_mov_b32_e32 v1, v164
	v_mov_b32_e32 v2, v165
	s_add_i32 s34, s34, s21
	s_and_b64 vcc, exec, s[4:5]
	v_add_u32_e32 v150, s34, v1
	v_ashrrev_i32_e32 v151, 31, v150
	v_lshl_add_u32 v148, v2, 3, s31
	v_lshlrev_b64 v[154:155], 12, v[150:151]
	v_lshl_add_u64 v[2:3], s[46:47], 0, v[154:155]
	v_ashrrev_i32_e32 v149, 31, v148
	v_lshl_add_u64 v[2:3], v[2:3], 0, v[148:149]
	global_load_dwordx2 v[158:159], v[2:3], off offset:2048
	global_load_dwordx2 v[160:161], v[2:3], off offset:2176
	s_mov_b32 s77, 0
	s_mov_b32 s76, 0x20000
	v_lshl_add_u64 v[246:247], v[2:3], 0, s[76:77]
	global_load_dwordx2 v[186:187], v[246:247], off offset:2048
	global_load_dwordx2 v[188:189], v[246:247], off offset:2176
	s_mov_b32 s76, 0x30000
	v_lshl_add_u64 v[246:247], v[2:3], 0, s[76:77]
	global_load_dwordx2 v[190:191], v[246:247], off offset:2048
	global_load_dwordx2 v[192:193], v[246:247], off offset:2176
	s_mov_b32 s76, 0x80000
	v_lshl_add_u64 v[246:247], v[2:3], 0, s[76:77]
	global_load_dwordx2 v[194:195], v[246:247], off offset:2048
	global_load_dwordx2 v[196:197], v[246:247], off offset:2176
	s_mov_b32 s76, 0x90000
	v_lshl_add_u64 v[246:247], v[2:3], 0, s[76:77]
	global_load_dwordx2 v[198:199], v[246:247], off offset:2048
	global_load_dwordx2 v[200:201], v[246:247], off offset:2176
	s_mov_b32 s76, 0xa0000
	v_lshl_add_u64 v[246:247], v[2:3], 0, s[76:77]
	global_load_dwordx2 v[202:203], v[246:247], off offset:2048
	global_load_dwordx2 v[204:205], v[246:247], off offset:2176
	s_mov_b32 s76, 0xb0000
	v_lshl_add_u64 v[246:247], v[2:3], 0, s[76:77]
	global_load_dwordx2 v[206:207], v[246:247], off offset:2048
	global_load_dwordx2 v[208:209], v[246:247], off offset:2176
	v_add_u32_e32 v2, 16, v150
	v_ashrrev_i32_e32 v3, 31, v2
	v_lshlrev_b64 v[156:157], 12, v[2:3]
	v_lshl_add_u64 v[2:3], s[46:47], 0, v[156:157]
	v_lshl_add_u64 v[162:163], v[2:3], 0, v[148:149]
	global_load_dwordx2 v[152:153], v[162:163], off offset:2048
	v_add_u32_e32 v168, 32, v150
	global_load_dwordx2 v[162:163], v[162:163], off offset:2176
	v_ashrrev_i32_e32 v169, 31, v168
	v_lshlrev_b64 v[2:3], 1, v[148:149]
	v_lshl_add_u64 v[170:171], s[50:51], 0, v[154:155]
	v_lshlrev_b64 v[154:155], 12, v[168:169]
	v_lshl_add_u64 v[168:169], v[170:171], 0, v[2:3]
	v_lshl_add_u64 v[170:171], s[46:47], 0, v[154:155]
	v_lshl_add_u64 v[170:171], v[170:171], 0, v[148:149]
	s_mov_b64 s[4:5], -1
	s_waitcnt vmcnt(0)
	v_cvt_f32_ubyte0_e32 v1, v158
	v_cvt_f32_ubyte0_e32 v151, v159
	v_cvt_f32_ubyte1_e32 v172, v158
	v_cvt_f32_ubyte1_e32 v173, v159
	v_cvt_f32_ubyte2_e32 v174, v158
	v_cvt_f32_ubyte2_e32 v175, v159
	v_cvt_f32_ubyte3_e32 v176, v158
	v_cvt_f32_ubyte3_e32 v177, v159
	v_cvt_f32_ubyte0_e32 v178, v160
	v_cvt_f32_ubyte0_e32 v179, v161
	v_cvt_f32_ubyte1_e32 v180, v160
	v_cvt_f32_ubyte1_e32 v181, v161
	v_cvt_f32_ubyte2_e32 v182, v160
	v_cvt_f32_ubyte2_e32 v183, v161
	v_cvt_f32_ubyte3_e32 v185, v161
	v_cvt_f32_ubyte3_e32 v184, v160
	v_max_f32_e32 v158, 0.5, v1
	v_max_f32_e32 v160, 0.5, v151
	v_max_f32_e32 v159, 0.5, v172
	v_max_f32_e32 v161, 0.5, v173
	v_max_f32_e32 v172, 0.5, v174
	v_max_f32_e32 v174, 0.5, v175
	v_max_f32_e32 v173, 0.5, v176
	v_max_f32_e32 v175, 0.5, v177
	v_max_f32_e32 v176, 0.5, v178
	v_max_f32_e32 v178, 0.5, v179
	v_max_f32_e32 v177, 0.5, v180
	v_max_f32_e32 v179, 0.5, v181
	v_max_f32_e32 v180, 0.5, v182
	v_max_f32_e32 v182, 0.5, v183
	v_max_f32_e32 v183, 0.5, v185
	v_max_f32_e32 v181, 0.5, v184
	v_pk_mul_f32 v[158:159], v[158:159], s[56:57] op_sel_hi:[1,0]
	v_pk_mul_f32 v[172:173], v[172:173], s[56:57] op_sel_hi:[1,0]
	v_pk_mul_f32 v[160:161], v[160:161], s[56:57] op_sel_hi:[1,0]
	v_pk_mul_f32 v[174:175], v[174:175], s[56:57] op_sel_hi:[1,0]
	v_pk_mul_f32 v[178:179], v[178:179], s[56:57] op_sel_hi:[1,0]
	v_pk_mul_f32 v[182:183], v[182:183], s[56:57] op_sel_hi:[1,0]
	v_pk_mul_f32 v[176:177], v[176:177], s[56:57] op_sel_hi:[1,0]
	v_pk_mul_f32 v[180:181], v[180:181], s[56:57] op_sel_hi:[1,0]
	v_pk_mul_f32 v[130:131], v[130:131], v[172:173]
	v_pk_mul_f32 v[128:129], v[128:129], v[158:159]
	v_pk_mul_f32 v[126:127], v[126:127], v[174:175]
	v_pk_mul_f32 v[124:125], v[124:125], v[160:161]
	v_pk_mul_f32 v[158:159], v[118:119], v[182:183]
	v_pk_mul_f32 v[160:161], v[116:117], v[178:179]
	v_cvt_pk_bf16_f32 v116, v128, v129
	v_cvt_pk_bf16_f32 v117, v130, v131
	v_cvt_pk_bf16_f32 v118, v124, v125
	v_cvt_pk_bf16_f32 v119, v126, v127
	v_pk_mul_f32 v[122:123], v[122:123], v[180:181]
	v_pk_mul_f32 v[120:121], v[120:121], v[176:177]
	global_store_dwordx4 v[168:169], v[116:119], off
	v_cvt_f32_ubyte0_e32 v1, v152
	v_cvt_f32_ubyte0_e32 v125, v153
	v_cvt_pk_bf16_f32 v116, v120, v121
	v_cvt_pk_bf16_f32 v117, v122, v123
	v_cvt_pk_bf16_f32 v118, v160, v161
	v_cvt_pk_bf16_f32 v119, v158, v159
	global_store_dwordx4 v[168:169], v[116:119], off offset:256
	s_nop 1
	v_mov_b64_e32 v[116:117], v[186:187]
	v_cvt_f32_ubyte1_e32 v127, v152
	v_cvt_f32_ubyte1_e32 v128, v153
	v_cvt_f32_ubyte2_e32 v129, v152
	v_cvt_f32_ubyte2_e32 v130, v153
	v_cvt_f32_ubyte3_e32 v131, v152
	v_cvt_f32_ubyte3_e32 v151, v153
	v_mov_b64_e32 v[152:153], v[188:189]
	v_add_u32_e32 v118, 48, v150
	v_lshl_add_u64 v[120:121], s[50:51], 0, v[156:157]
	v_cvt_f32_ubyte0_e32 v157, v163
	v_cvt_f32_ubyte1_e32 v159, v162
	v_cvt_f32_ubyte1_e32 v160, v163
	v_cvt_f32_ubyte2_e32 v168, v163
	v_cvt_f32_ubyte3_e32 v163, v163
	v_ashrrev_i32_e32 v119, 31, v118
	v_cvt_f32_ubyte0_e32 v156, v162
	v_cvt_f32_ubyte2_e32 v161, v162
	v_cvt_f32_ubyte3_e32 v169, v162
	v_max_f32_e32 v124, 0.5, v1
	v_max_f32_e32 v126, 0.5, v125
	v_max_f32_e32 v125, 0.5, v127
	v_max_f32_e32 v127, 0.5, v128
	v_max_f32_e32 v128, 0.5, v129
	v_max_f32_e32 v130, 0.5, v130
	v_max_f32_e32 v129, 0.5, v131
; __device__ __forceinline__ unsigned cvt_pk_bf16(float lo, float hi) { unsigned r; asm volatile("v_cvt_pk_bf16_f32 %0, %1, %2" : "=v"(r) : "v"(lo), "v"(hi)); return r; }
;     __device__ __forceinline__ void operator()(EPI_ARGS) const {
;     ...
;         for (int g = 0; g < 8; ++g) {
;             const int ai = g >> 2, m = g & 3, row = ROW_OF(ai, m);
;             if (g < 7) {
; #pragma unroll
;                 for (int bj = 0; bj < 2; ++bj) gn[bj] = *(const u32x2*)(gates + (size_t)ROW_OF((g + 1) >> 2, (g + 1) & 3) * (2 * D) + D + col0 + bj * 128);
;             }
; #pragma unroll
;             for (int bj = 0; bj < 2; ++bj) {
;                 const unsigned b0 = gc[bj].x, b1 = gc[bj].y;
;                 f32x4 g0, g1;
; #pragma unroll
;                 for (int j = 0; j < 4; ++j) { g0[j] = fmaxf((float)((b0 >> (8 * j)) & 0xff), 0.5f) * (1.0f / 255.0f); g1[j] = fmaxf((float)((b1 >> (8 * j)) & 0xff), 0.5f) * (1.0f / 255.0f); }
;                 const f32x4 v0 = acc[ai][bj][m][0] * g0, v1 = acc[ai][bj][m][1] * g1;
;                 u32x4 w; w.x = cvt_pk_bf16(v0[0], v0[1]); w.y = cvt_pk_bf16(v0[2], v0[3]); w.z = cvt_pk_bf16(v1[0], v1[1]); w.w = cvt_pk_bf16(v1[2], v1[3]);
;                 *(u32x4*)(merged + (size_t)row * D + col0 + bj * 128) = w;
;             }
;             if (g < 7) { gc[0] = gn[0]; gc[1] = gn[1]; }
	v_max_f32_e32 v131, 0.5, v151
	v_max_f32_e32 v158, 0.5, v157
	v_max_f32_e32 v157, 0.5, v159
	v_max_f32_e32 v159, 0.5, v160
	v_max_f32_e32 v162, 0.5, v168
	v_max_f32_e32 v163, 0.5, v163
	v_lshlrev_b64 v[118:119], 12, v[118:119]
	v_max_f32_e32 v156, 0.5, v156
	v_max_f32_e32 v160, 0.5, v161
	v_max_f32_e32 v161, 0.5, v169
	v_pk_mul_f32 v[124:125], v[124:125], s[56:57] op_sel_hi:[1,0]
	v_pk_mul_f32 v[128:129], v[128:129], s[56:57] op_sel_hi:[1,0]
	v_pk_mul_f32 v[126:127], v[126:127], s[56:57] op_sel_hi:[1,0]
	v_pk_mul_f32 v[130:131], v[130:131], s[56:57] op_sel_hi:[1,0]
	v_pk_mul_f32 v[158:159], v[158:159], s[56:57] op_sel_hi:[1,0]
	v_pk_mul_f32 v[162:163], v[162:163], s[56:57] op_sel_hi:[1,0]
	v_lshl_add_u64 v[122:123], s[46:47], 0, v[118:119]
	v_lshl_add_u64 v[120:121], v[120:121], 0, v[2:3]
	v_pk_mul_f32 v[156:157], v[156:157], s[56:57] op_sel_hi:[1,0]
	v_pk_mul_f32 v[160:161], v[160:161], s[56:57] op_sel_hi:[1,0]
	v_pk_mul_f32 v[114:115], v[114:115], v[128:129]
	v_pk_mul_f32 v[112:113], v[112:113], v[124:125]
	v_pk_mul_f32 v[110:111], v[110:111], v[130:131]
	v_pk_mul_f32 v[108:109], v[108:109], v[126:127]
	v_pk_mul_f32 v[124:125], v[102:103], v[162:163]
	v_pk_mul_f32 v[126:127], v[100:101], v[158:159]
	v_cvt_pk_bf16_f32 v100, v112, v113
	v_cvt_pk_bf16_f32 v101, v114, v115
	v_cvt_pk_bf16_f32 v102, v108, v109
	v_cvt_pk_bf16_f32 v103, v110, v111
	v_lshl_add_u64 v[122:123], v[122:123], 0, v[148:149]
	v_pk_mul_f32 v[106:107], v[106:107], v[160:161]
	v_pk_mul_f32 v[104:105], v[104:105], v[156:157]
	global_store_dwordx4 v[120:121], v[100:103], off
	v_cvt_f32_ubyte0_e32 v1, v116
	v_cvt_pk_bf16_f32 v100, v104, v105
	v_cvt_pk_bf16_f32 v101, v106, v107
	v_cvt_pk_bf16_f32 v102, v126, v127
	v_cvt_pk_bf16_f32 v103, v124, v125
	global_store_dwordx4 v[120:121], v[100:103], off offset:256
	s_nop 1
	v_mov_b64_e32 v[100:101], v[190:191]
	s_nop 0
	s_nop 1
	v_mov_b64_e32 v[102:103], v[192:193]
	v_cvt_f32_ubyte0_e32 v105, v117
	v_cvt_f32_ubyte1_e32 v107, v116
	v_cvt_f32_ubyte1_e32 v108, v117
	v_cvt_f32_ubyte2_e32 v109, v116
	v_cvt_f32_ubyte2_e32 v110, v117
	v_cvt_f32_ubyte3_e32 v111, v116
	v_cvt_f32_ubyte3_e32 v112, v117
	v_max_f32_e32 v104, 0.5, v1
	v_max_f32_e32 v106, 0.5, v105
	v_max_f32_e32 v105, 0.5, v107
	v_max_f32_e32 v107, 0.5, v108
	v_max_f32_e32 v108, 0.5, v109
	v_max_f32_e32 v110, 0.5, v110
	v_max_f32_e32 v109, 0.5, v111
	v_max_f32_e32 v111, 0.5, v112
	v_pk_mul_f32 v[104:105], v[104:105], s[56:57] op_sel_hi:[1,0]
	v_pk_mul_f32 v[106:107], v[106:107], s[56:57] op_sel_hi:[1,0]
	v_pk_mul_f32 v[110:111], v[110:111], s[56:57] op_sel_hi:[1,0]
	v_pk_mul_f32 v[96:97], v[96:97], v[104:105]
	v_pk_mul_f32 v[104:105], v[94:95], v[110:111]
	v_pk_mul_f32 v[94:95], v[92:93], v[106:107]
	v_cvt_pk_bf16_f32 v92, v96, v97
	v_lshl_add_u64 v[96:97], s[50:51], 0, v[154:155]
	v_pk_mul_f32 v[108:109], v[108:109], s[56:57] op_sel_hi:[1,0]
	v_lshl_add_u64 v[96:97], v[96:97], 0, v[2:3]
	v_cvt_f32_ubyte0_e32 v1, v152
	v_pk_mul_f32 v[98:99], v[98:99], v[108:109]
	s_nop 0
	v_cvt_pk_bf16_f32 v93, v98, v99
	v_cvt_pk_bf16_f32 v94, v94, v95
	v_cvt_pk_bf16_f32 v95, v104, v105
	global_store_dwordx4 v[96:97], v[92:95], off
	s_nop 1
	v_max_f32_e32 v92, 0.5, v1
	v_cvt_f32_ubyte0_e32 v1, v153
	v_max_f32_e32 v94, 0.5, v1
	v_cvt_f32_ubyte1_e32 v1, v152
	v_max_f32_e32 v93, 0.5, v1
	v_cvt_f32_ubyte1_e32 v1, v153
	v_max_f32_e32 v95, 0.5, v1
	v_cvt_f32_ubyte2_e32 v1, v152
	v_max_f32_e32 v98, 0.5, v1
	v_cvt_f32_ubyte2_e32 v1, v153
	v_max_f32_e32 v104, 0.5, v1
	v_cvt_f32_ubyte3_e32 v1, v152
	v_max_f32_e32 v99, 0.5, v1
	v_cvt_f32_ubyte3_e32 v1, v153
	v_max_f32_e32 v105, 0.5, v1
	v_pk_mul_f32 v[92:93], v[92:93], s[56:57] op_sel_hi:[1,0]
	v_pk_mul_f32 v[98:99], v[98:99], s[56:57] op_sel_hi:[1,0]
	v_pk_mul_f32 v[94:95], v[94:95], s[56:57] op_sel_hi:[1,0]
	v_pk_mul_f32 v[104:105], v[104:105], s[56:57] op_sel_hi:[1,0]
	v_pk_mul_f32 v[90:91], v[90:91], v[98:99]
	v_pk_mul_f32 v[88:89], v[88:89], v[92:93]
	v_pk_mul_f32 v[92:93], v[86:87], v[104:105]
	v_pk_mul_f32 v[86:87], v[84:85], v[94:95]
	v_cvt_pk_bf16_f32 v84, v88, v89
	v_cvt_pk_bf16_f32 v85, v90, v91
	v_cvt_f32_ubyte0_e32 v1, v100
	v_cvt_pk_bf16_f32 v86, v86, v87
	v_cvt_pk_bf16_f32 v87, v92, v93
	global_store_dwordx4 v[96:97], v[84:87], off offset:256
	v_max_f32_e32 v90, 0.5, v1
	v_cvt_f32_ubyte0_e32 v1, v101
	v_add_u32_e32 v84, 0x80, v150
	v_ashrrev_i32_e32 v85, 31, v84
	v_max_f32_e32 v92, 0.5, v1
	v_cvt_f32_ubyte1_e32 v1, v100
	v_lshlrev_b64 v[84:85], 12, v[84:85]
	v_max_f32_e32 v91, 0.5, v1
	v_cvt_f32_ubyte1_e32 v1, v101
	v_lshl_add_u64 v[86:87], s[46:47], 0, v[84:85]
	v_max_f32_e32 v93, 0.5, v1
	v_cvt_f32_ubyte2_e32 v1, v100
	v_lshl_add_u64 v[86:87], v[86:87], 0, v[148:149]
	v_max_f32_e32 v94, 0.5, v1
	v_cvt_f32_ubyte2_e32 v1, v101
	v_mov_b64_e32 v[88:89], v[194:195]
	s_nop 0
	v_mov_b64_e32 v[86:87], v[196:197]
	v_max_f32_e32 v96, 0.5, v1
	v_cvt_f32_ubyte3_e32 v1, v100
	v_max_f32_e32 v95, 0.5, v1
	v_cvt_f32_ubyte3_e32 v1, v101
	v_pk_mul_f32 v[90:91], v[90:91], s[56:57] op_sel_hi:[1,0]
	v_max_f32_e32 v97, 0.5, v1
	v_pk_mul_f32 v[92:93], v[92:93], s[56:57] op_sel_hi:[1,0]
	v_pk_mul_f32 v[96:97], v[96:97], s[56:57] op_sel_hi:[1,0]
	v_pk_mul_f32 v[80:81], v[80:81], v[90:91]
	v_pk_mul_f32 v[90:91], v[78:79], v[96:97]
	v_pk_mul_f32 v[78:79], v[76:77], v[92:93]
	v_cvt_pk_bf16_f32 v76, v80, v81
	v_lshl_add_u64 v[80:81], s[50:51], 0, v[118:119]
	v_pk_mul_f32 v[94:95], v[94:95], s[56:57] op_sel_hi:[1,0]
	v_lshl_add_u64 v[80:81], v[80:81], 0, v[2:3]
	v_cvt_f32_ubyte0_e32 v1, v102
	v_pk_mul_f32 v[82:83], v[82:83], v[94:95]
	s_nop 0
	v_cvt_pk_bf16_f32 v77, v82, v83
	v_cvt_pk_bf16_f32 v78, v78, v79
	v_cvt_pk_bf16_f32 v79, v90, v91
	global_store_dwordx4 v[80:81], v[76:79], off
; __device__ __forceinline__ unsigned cvt_pk_bf16(float lo, float hi) { unsigned r; asm volatile("v_cvt_pk_bf16_f32 %0, %1, %2" : "=v"(r) : "v"(lo), "v"(hi)); return r; }
;     __device__ __forceinline__ void operator()(EPI_ARGS) const {
;     ...
;         for (int g = 0; g < 8; ++g) {
;             const int ai = g >> 2, m = g & 3, row = ROW_OF(ai, m);
;             if (g < 7) {
; #pragma unroll
;                 for (int bj = 0; bj < 2; ++bj) gn[bj] = *(const u32x2*)(gates + (size_t)ROW_OF((g + 1) >> 2, (g + 1) & 3) * (2 * D) + D + col0 + bj * 128);
;             }
; #pragma unroll
;             for (int bj = 0; bj < 2; ++bj) {
;                 const unsigned b0 = gc[bj].x, b1 = gc[bj].y;
;                 f32x4 g0, g1;
; #pragma unroll
;                 for (int j = 0; j < 4; ++j) { g0[j] = fmaxf((float)((b0 >> (8 * j)) & 0xff), 0.5f) * (1.0f / 255.0f); g1[j] = fmaxf((float)((b1 >> (8 * j)) & 0xff), 0.5f) * (1.0f / 255.0f); }
;                 const f32x4 v0 = acc[ai][bj][m][0] * g0, v1 = acc[ai][bj][m][1] * g1;
;                 u32x4 w; w.x = cvt_pk_bf16(v0[0], v0[1]); w.y = cvt_pk_bf16(v0[2], v0[3]); w.z = cvt_pk_bf16(v1[0], v1[1]); w.w = cvt_pk_bf16(v1[2], v1[3]);
;                 *(u32x4*)(merged + (size_t)row * D + col0 + bj * 128) = w;
;             }
;             if (g < 7) { gc[0] = gn[0]; gc[1] = gn[1]; }
	s_nop 1
	v_max_f32_e32 v76, 0.5, v1
	v_cvt_f32_ubyte0_e32 v1, v103
	v_max_f32_e32 v78, 0.5, v1
	v_cvt_f32_ubyte1_e32 v1, v102
	v_max_f32_e32 v77, 0.5, v1
	v_cvt_f32_ubyte1_e32 v1, v103
	v_max_f32_e32 v79, 0.5, v1
	v_cvt_f32_ubyte2_e32 v1, v102
	v_max_f32_e32 v82, 0.5, v1
	v_cvt_f32_ubyte2_e32 v1, v103
	v_max_f32_e32 v90, 0.5, v1
	v_cvt_f32_ubyte3_e32 v1, v102
	v_max_f32_e32 v83, 0.5, v1
	v_cvt_f32_ubyte3_e32 v1, v103
	v_max_f32_e32 v91, 0.5, v1
	v_pk_mul_f32 v[76:77], v[76:77], s[56:57] op_sel_hi:[1,0]
	v_pk_mul_f32 v[78:79], v[78:79], s[56:57] op_sel_hi:[1,0]
	v_pk_mul_f32 v[90:91], v[90:91], s[56:57] op_sel_hi:[1,0]
	v_pk_mul_f32 v[82:83], v[82:83], s[56:57] op_sel_hi:[1,0]
	v_pk_mul_f32 v[72:73], v[72:73], v[76:77]
	v_pk_mul_f32 v[76:77], v[70:71], v[90:91]
	v_pk_mul_f32 v[70:71], v[68:69], v[78:79]
	v_cvt_pk_bf16_f32 v68, v72, v73
	v_pk_mul_f32 v[74:75], v[74:75], v[82:83]
	v_cvt_f32_ubyte0_e32 v1, v88
	v_cvt_pk_bf16_f32 v69, v74, v75
	v_cvt_pk_bf16_f32 v70, v70, v71
	v_cvt_pk_bf16_f32 v71, v76, v77
	global_store_dwordx4 v[80:81], v[68:71], off offset:256
	v_max_f32_e32 v74, 0.5, v1
	v_cvt_f32_ubyte0_e32 v1, v89
	v_add_u32_e32 v68, 0x90, v150
	v_ashrrev_i32_e32 v69, 31, v68
	v_lshlrev_b64 v[68:69], 12, v[68:69]
	v_lshl_add_u64 v[70:71], s[46:47], 0, v[68:69]
	v_lshl_add_u64 v[70:71], v[70:71], 0, v[148:149]
	v_mov_b64_e32 v[72:73], v[198:199]
	s_nop 0
	v_mov_b64_e32 v[70:71], v[200:201]
	v_max_f32_e32 v76, 0.5, v1
	v_cvt_f32_ubyte1_e32 v1, v88
	v_max_f32_e32 v75, 0.5, v1
	v_cvt_f32_ubyte1_e32 v1, v89
	v_max_f32_e32 v77, 0.5, v1
	v_cvt_f32_ubyte2_e32 v1, v88
	v_max_f32_e32 v78, 0.5, v1
	v_cvt_f32_ubyte2_e32 v1, v89
	v_max_f32_e32 v80, 0.5, v1
	v_cvt_f32_ubyte3_e32 v1, v88
	v_max_f32_e32 v79, 0.5, v1
	v_cvt_f32_ubyte3_e32 v1, v89
	v_pk_mul_f32 v[74:75], v[74:75], s[56:57] op_sel_hi:[1,0]
	v_max_f32_e32 v81, 0.5, v1
	v_pk_mul_f32 v[76:77], v[76:77], s[56:57] op_sel_hi:[1,0]
	v_pk_mul_f32 v[80:81], v[80:81], s[56:57] op_sel_hi:[1,0]
	v_pk_mul_f32 v[64:65], v[64:65], v[74:75]
	v_pk_mul_f32 v[74:75], v[62:63], v[80:81]
	v_pk_mul_f32 v[62:63], v[60:61], v[76:77]
	v_cvt_pk_bf16_f32 v60, v64, v65
	v_lshl_add_u64 v[64:65], s[50:51], 0, v[84:85]
	v_pk_mul_f32 v[78:79], v[78:79], s[56:57] op_sel_hi:[1,0]
	v_lshl_add_u64 v[64:65], v[64:65], 0, v[2:3]
	v_cvt_f32_ubyte0_e32 v1, v86
	v_pk_mul_f32 v[66:67], v[66:67], v[78:79]
	s_nop 0
	v_cvt_pk_bf16_f32 v61, v66, v67
	v_cvt_pk_bf16_f32 v62, v62, v63
	v_cvt_pk_bf16_f32 v63, v74, v75
	global_store_dwordx4 v[64:65], v[60:63], off
	s_nop 1
	v_max_f32_e32 v60, 0.5, v1
	v_cvt_f32_ubyte0_e32 v1, v87
	v_max_f32_e32 v62, 0.5, v1
	v_cvt_f32_ubyte1_e32 v1, v86
	v_max_f32_e32 v61, 0.5, v1
	v_cvt_f32_ubyte1_e32 v1, v87
	v_max_f32_e32 v63, 0.5, v1
	v_cvt_f32_ubyte2_e32 v1, v86
	v_max_f32_e32 v66, 0.5, v1
	v_cvt_f32_ubyte2_e32 v1, v87
	v_max_f32_e32 v74, 0.5, v1
	v_cvt_f32_ubyte3_e32 v1, v86
	v_max_f32_e32 v67, 0.5, v1
	v_cvt_f32_ubyte3_e32 v1, v87
	v_max_f32_e32 v75, 0.5, v1
	v_pk_mul_f32 v[60:61], v[60:61], s[56:57] op_sel_hi:[1,0]
	v_pk_mul_f32 v[66:67], v[66:67], s[56:57] op_sel_hi:[1,0]
	v_pk_mul_f32 v[62:63], v[62:63], s[56:57] op_sel_hi:[1,0]
	v_pk_mul_f32 v[74:75], v[74:75], s[56:57] op_sel_hi:[1,0]
	v_pk_mul_f32 v[58:59], v[58:59], v[66:67]
	v_pk_mul_f32 v[56:57], v[56:57], v[60:61]
	v_pk_mul_f32 v[60:61], v[54:55], v[74:75]
	v_pk_mul_f32 v[54:55], v[52:53], v[62:63]
	v_cvt_pk_bf16_f32 v52, v56, v57
	v_cvt_pk_bf16_f32 v53, v58, v59
	v_cvt_f32_ubyte0_e32 v1, v72
	v_cvt_pk_bf16_f32 v54, v54, v55
	v_cvt_pk_bf16_f32 v55, v60, v61
	global_store_dwordx4 v[64:65], v[52:55], off offset:256
	v_max_f32_e32 v58, 0.5, v1
	v_cvt_f32_ubyte0_e32 v1, v73
	v_add_u32_e32 v52, 0xa0, v150
	v_ashrrev_i32_e32 v53, 31, v52
	v_max_f32_e32 v60, 0.5, v1
	v_cvt_f32_ubyte1_e32 v1, v72
	v_lshlrev_b64 v[52:53], 12, v[52:53]
	v_max_f32_e32 v59, 0.5, v1
	v_cvt_f32_ubyte1_e32 v1, v73
	v_lshl_add_u64 v[54:55], s[46:47], 0, v[52:53]
	v_max_f32_e32 v61, 0.5, v1
	v_cvt_f32_ubyte2_e32 v1, v72
	v_lshl_add_u64 v[54:55], v[54:55], 0, v[148:149]
	v_max_f32_e32 v62, 0.5, v1
	v_cvt_f32_ubyte2_e32 v1, v73
	v_mov_b64_e32 v[56:57], v[202:203]
	s_nop 0
	v_mov_b64_e32 v[54:55], v[204:205]
	v_max_f32_e32 v64, 0.5, v1
	v_cvt_f32_ubyte3_e32 v1, v72
	v_max_f32_e32 v63, 0.5, v1
	v_cvt_f32_ubyte3_e32 v1, v73
	v_pk_mul_f32 v[58:59], v[58:59], s[56:57] op_sel_hi:[1,0]
	v_max_f32_e32 v65, 0.5, v1
	v_pk_mul_f32 v[60:61], v[60:61], s[56:57] op_sel_hi:[1,0]
	v_pk_mul_f32 v[64:65], v[64:65], s[56:57] op_sel_hi:[1,0]
	v_pk_mul_f32 v[48:49], v[48:49], v[58:59]
	v_pk_mul_f32 v[58:59], v[46:47], v[64:65]
	v_pk_mul_f32 v[46:47], v[44:45], v[60:61]
	v_cvt_pk_bf16_f32 v44, v48, v49
	v_lshl_add_u64 v[48:49], s[50:51], 0, v[68:69]
	v_pk_mul_f32 v[62:63], v[62:63], s[56:57] op_sel_hi:[1,0]
	v_lshl_add_u64 v[48:49], v[48:49], 0, v[2:3]
	v_cvt_f32_ubyte0_e32 v1, v70
	v_pk_mul_f32 v[50:51], v[50:51], v[62:63]
	s_nop 0
	v_cvt_pk_bf16_f32 v45, v50, v51
	v_cvt_pk_bf16_f32 v46, v46, v47
	v_cvt_pk_bf16_f32 v47, v58, v59
	global_store_dwordx4 v[48:49], v[44:47], off
	s_nop 1
	v_max_f32_e32 v44, 0.5, v1
	v_cvt_f32_ubyte0_e32 v1, v71
	v_max_f32_e32 v46, 0.5, v1
	v_cvt_f32_ubyte1_e32 v1, v70
	v_max_f32_e32 v45, 0.5, v1
	v_cvt_f32_ubyte1_e32 v1, v71
	v_max_f32_e32 v47, 0.5, v1
	v_cvt_f32_ubyte2_e32 v1, v70
	v_max_f32_e32 v50, 0.5, v1
	v_cvt_f32_ubyte2_e32 v1, v71
	v_max_f32_e32 v58, 0.5, v1
	v_cvt_f32_ubyte3_e32 v1, v70
	v_max_f32_e32 v51, 0.5, v1
	v_cvt_f32_ubyte3_e32 v1, v71
; __device__ __forceinline__ unsigned cvt_pk_bf16(float lo, float hi) { unsigned r; asm volatile("v_cvt_pk_bf16_f32 %0, %1, %2" : "=v"(r) : "v"(lo), "v"(hi)); return r; }
; #define PG8_BAR __builtin_amdgcn_s_barrier()
; template <class Epi, class Sched>
; __device__ __forceinline__ void gemm_phase(LAS unsigned char* lds, const Gemm g, const Sched& S, const Epi& E) {
;     ...
;         if (!has_next) break;
; #pragma unroll
;         for (int a = 0; a < 2; ++a)
; #pragma unroll
;             for (int b = 0; b < 2; ++b)
; #pragma unroll
;                 for (int m = 0; m < 4; ++m)
; #pragma unroll
;                     for (int n = 0; n < 2; ++n) acc[a][b][m][n] = (f32x4){0.f, 0.f, 0.f, 0.f};
;         cur = nxt; cA = nA; cB = nB; ++ui;
;         if (wr == 1) PG8_BAR;
;     __device__ __forceinline__ void operator()(EPI_ARGS) const {
;     ...
;         for (int g = 0; g < 8; ++g) {
;             const int ai = g >> 2, m = g & 3, row = ROW_OF(ai, m);
;             if (g < 7) {
; #pragma unroll
;                 for (int bj = 0; bj < 2; ++bj) gn[bj] = *(const u32x2*)(gates + (size_t)ROW_OF((g + 1) >> 2, (g + 1) & 3) * (2 * D) + D + col0 + bj * 128);
;             }
; #pragma unroll
;             for (int bj = 0; bj < 2; ++bj) {
;                 const unsigned b0 = gc[bj].x, b1 = gc[bj].y;
;                 f32x4 g0, g1;
; #pragma unroll
;                 for (int j = 0; j < 4; ++j) { g0[j] = fmaxf((float)((b0 >> (8 * j)) & 0xff), 0.5f) * (1.0f / 255.0f); g1[j] = fmaxf((float)((b1 >> (8 * j)) & 0xff), 0.5f) * (1.0f / 255.0f); }
;                 const f32x4 v0 = acc[ai][bj][m][0] * g0, v1 = acc[ai][bj][m][1] * g1;
;                 u32x4 w; w.x = cvt_pk_bf16(v0[0], v0[1]); w.y = cvt_pk_bf16(v0[2], v0[3]); w.z = cvt_pk_bf16(v1[0], v1[1]); w.w = cvt_pk_bf16(v1[2], v1[3]);
;                 *(u32x4*)(merged + (size_t)row * D + col0 + bj * 128) = w;
;             }
;             if (g < 7) { gc[0] = gn[0]; gc[1] = gn[1]; }
	v_max_f32_e32 v59, 0.5, v1
	v_pk_mul_f32 v[44:45], v[44:45], s[56:57] op_sel_hi:[1,0]
	v_pk_mul_f32 v[46:47], v[46:47], s[56:57] op_sel_hi:[1,0]
	v_pk_mul_f32 v[58:59], v[58:59], s[56:57] op_sel_hi:[1,0]
	v_pk_mul_f32 v[50:51], v[50:51], s[56:57] op_sel_hi:[1,0]
	v_pk_mul_f32 v[40:41], v[40:41], v[44:45]
	v_pk_mul_f32 v[44:45], v[38:39], v[58:59]
	v_pk_mul_f32 v[38:39], v[36:37], v[46:47]
	v_cvt_pk_bf16_f32 v36, v40, v41
	v_pk_mul_f32 v[42:43], v[42:43], v[50:51]
	v_cvt_f32_ubyte0_e32 v1, v56
	v_cvt_pk_bf16_f32 v37, v42, v43
	v_cvt_pk_bf16_f32 v38, v38, v39
	v_cvt_pk_bf16_f32 v39, v44, v45
	global_store_dwordx4 v[48:49], v[36:39], off offset:256
	v_max_f32_e32 v42, 0.5, v1
	v_cvt_f32_ubyte0_e32 v1, v57
	v_add_u32_e32 v36, 0xb0, v150
	v_ashrrev_i32_e32 v37, 31, v36
	v_lshlrev_b64 v[36:37], 12, v[36:37]
	v_lshl_add_u64 v[38:39], s[46:47], 0, v[36:37]
	v_lshl_add_u64 v[38:39], v[38:39], 0, v[148:149]
	v_mov_b64_e32 v[40:41], v[206:207]
	s_nop 0
	v_mov_b64_e32 v[38:39], v[208:209]
	v_max_f32_e32 v44, 0.5, v1
	v_cvt_f32_ubyte1_e32 v1, v56
	v_max_f32_e32 v43, 0.5, v1
	v_cvt_f32_ubyte1_e32 v1, v57
	v_max_f32_e32 v45, 0.5, v1
	v_cvt_f32_ubyte2_e32 v1, v56
	v_max_f32_e32 v46, 0.5, v1
	v_cvt_f32_ubyte2_e32 v1, v57
	v_max_f32_e32 v48, 0.5, v1
	v_cvt_f32_ubyte3_e32 v1, v56
	v_max_f32_e32 v47, 0.5, v1
	v_cvt_f32_ubyte3_e32 v1, v57
	v_pk_mul_f32 v[42:43], v[42:43], s[56:57] op_sel_hi:[1,0]
	v_max_f32_e32 v49, 0.5, v1
	v_pk_mul_f32 v[44:45], v[44:45], s[56:57] op_sel_hi:[1,0]
	v_pk_mul_f32 v[48:49], v[48:49], s[56:57] op_sel_hi:[1,0]
	v_pk_mul_f32 v[32:33], v[32:33], v[42:43]
	v_pk_mul_f32 v[42:43], v[30:31], v[48:49]
	v_pk_mul_f32 v[30:31], v[28:29], v[44:45]
	v_cvt_pk_bf16_f32 v28, v32, v33
	v_lshl_add_u64 v[32:33], s[50:51], 0, v[52:53]
	v_pk_mul_f32 v[46:47], v[46:47], s[56:57] op_sel_hi:[1,0]
	v_lshl_add_u64 v[32:33], v[32:33], 0, v[2:3]
	v_cvt_f32_ubyte0_e32 v1, v54
	v_pk_mul_f32 v[34:35], v[34:35], v[46:47]
	s_nop 0
	v_cvt_pk_bf16_f32 v29, v34, v35
	v_cvt_pk_bf16_f32 v30, v30, v31
	v_cvt_pk_bf16_f32 v31, v42, v43
	global_store_dwordx4 v[32:33], v[28:31], off
	s_nop 1
	v_max_f32_e32 v28, 0.5, v1
	v_cvt_f32_ubyte0_e32 v1, v55
	v_max_f32_e32 v30, 0.5, v1
	v_cvt_f32_ubyte1_e32 v1, v54
	v_max_f32_e32 v29, 0.5, v1
	v_cvt_f32_ubyte1_e32 v1, v55
	v_max_f32_e32 v31, 0.5, v1
	v_cvt_f32_ubyte2_e32 v1, v54
	v_max_f32_e32 v34, 0.5, v1
	v_cvt_f32_ubyte2_e32 v1, v55
	v_max_f32_e32 v42, 0.5, v1
	v_cvt_f32_ubyte3_e32 v1, v54
	v_max_f32_e32 v35, 0.5, v1
	v_cvt_f32_ubyte3_e32 v1, v55
	v_max_f32_e32 v43, 0.5, v1
	v_pk_mul_f32 v[28:29], v[28:29], s[56:57] op_sel_hi:[1,0]
	v_pk_mul_f32 v[30:31], v[30:31], s[56:57] op_sel_hi:[1,0]
	v_pk_mul_f32 v[42:43], v[42:43], s[56:57] op_sel_hi:[1,0]
	v_pk_mul_f32 v[34:35], v[34:35], s[56:57] op_sel_hi:[1,0]
	v_pk_mul_f32 v[24:25], v[24:25], v[28:29]
	v_pk_mul_f32 v[28:29], v[22:23], v[42:43]
	v_pk_mul_f32 v[22:23], v[20:21], v[30:31]
	v_cvt_pk_bf16_f32 v20, v24, v25
	v_pk_mul_f32 v[26:27], v[26:27], v[34:35]
	v_cvt_f32_ubyte0_e32 v1, v40
	v_cvt_pk_bf16_f32 v21, v26, v27
	v_cvt_pk_bf16_f32 v22, v22, v23
	v_cvt_pk_bf16_f32 v23, v28, v29
	global_store_dwordx4 v[32:33], v[20:23], off offset:256
	s_nop 1
	v_max_f32_e32 v20, 0.5, v1
	v_cvt_f32_ubyte0_e32 v1, v41
	v_max_f32_e32 v22, 0.5, v1
	v_cvt_f32_ubyte1_e32 v1, v40
	v_max_f32_e32 v21, 0.5, v1
	v_cvt_f32_ubyte1_e32 v1, v41
	v_max_f32_e32 v23, 0.5, v1
	v_cvt_f32_ubyte2_e32 v1, v40
	v_max_f32_e32 v24, 0.5, v1
	v_cvt_f32_ubyte2_e32 v1, v41
	v_max_f32_e32 v26, 0.5, v1
	v_cvt_f32_ubyte3_e32 v1, v40
	v_max_f32_e32 v25, 0.5, v1
	v_cvt_f32_ubyte3_e32 v1, v41
	v_pk_mul_f32 v[20:21], v[20:21], s[56:57] op_sel_hi:[1,0]
	v_max_f32_e32 v27, 0.5, v1
	v_pk_mul_f32 v[22:23], v[22:23], s[56:57] op_sel_hi:[1,0]
	v_pk_mul_f32 v[26:27], v[26:27], s[56:57] op_sel_hi:[1,0]
	v_pk_mul_f32 v[16:17], v[16:17], v[20:21]
	v_pk_mul_f32 v[20:21], v[14:15], v[26:27]
	v_pk_mul_f32 v[14:15], v[12:13], v[22:23]
	v_cvt_pk_bf16_f32 v12, v16, v17
	v_lshl_add_u64 v[16:17], s[50:51], 0, v[36:37]
	v_cvt_f32_ubyte0_e32 v1, v38
	v_pk_mul_f32 v[24:25], v[24:25], s[56:57] op_sel_hi:[1,0]
	v_lshl_add_u64 v[16:17], v[16:17], 0, v[2:3]
	v_max_f32_e32 v2, 0.5, v1
	v_cvt_f32_ubyte0_e32 v1, v39
	v_pk_mul_f32 v[18:19], v[18:19], v[24:25]
	s_nop 0
	v_cvt_pk_bf16_f32 v13, v18, v19
	v_cvt_pk_bf16_f32 v14, v14, v15
	v_cvt_pk_bf16_f32 v15, v20, v21
	global_store_dwordx4 v[16:17], v[12:15], off
	s_nop 1
	v_max_f32_e32 v12, 0.5, v1
	v_cvt_f32_ubyte1_e32 v1, v38
	v_max_f32_e32 v3, 0.5, v1
	v_cvt_f32_ubyte1_e32 v1, v39
	v_max_f32_e32 v13, 0.5, v1
	v_cvt_f32_ubyte2_e32 v1, v38
	v_max_f32_e32 v14, 0.5, v1
	v_cvt_f32_ubyte2_e32 v1, v39
	v_max_f32_e32 v18, 0.5, v1
	v_cvt_f32_ubyte3_e32 v1, v38
	v_max_f32_e32 v15, 0.5, v1
	v_cvt_f32_ubyte3_e32 v1, v39
	v_pk_mul_f32 v[2:3], v[2:3], s[56:57] op_sel_hi:[1,0]
	v_max_f32_e32 v19, 0.5, v1
	v_pk_mul_f32 v[12:13], v[12:13], s[56:57] op_sel_hi:[1,0]
	v_pk_mul_f32 v[14:15], v[14:15], s[56:57] op_sel_hi:[1,0]
	v_pk_mul_f32 v[18:19], v[18:19], s[56:57] op_sel_hi:[1,0]
	v_pk_mul_f32 v[2:3], v[8:9], v[2:3]
	v_pk_mul_f32 v[4:5], v[4:5], v[12:13]
	v_pk_mul_f32 v[10:11], v[10:11], v[14:15]
	v_pk_mul_f32 v[6:7], v[6:7], v[18:19]
	v_cvt_pk_bf16_f32 v2, v2, v3
	v_cvt_pk_bf16_f32 v3, v10, v11
	v_cvt_pk_bf16_f32 v4, v4, v5
	s_nop 0
	v_cvt_pk_bf16_f32 v5, v6, v7
	global_store_dwordx4 v[16:17], v[2:5], off offset:256
	s_cbranch_vccnz .LBB0_740
	s_andn2_b64 vcc, exec, s[38:39]
	s_cbranch_vccnz .LBB0_739
	s_barrier
	s_branch .LBB0_739
